# P5 single-read variant + next row group prefetched into the kept registers while the softmax of the current one runs
# baseline (speedup 1.0000x reference)
.Lp5n_loop:
	s_and_b32 s51, s98, 1
	s_and_b32 s101, s98, 6
	s_lshl_b32 s61, s100, 3
	s_add_i32 s61, s61, s101
	s_lshl_b32 s62, s61, 4
	s_lshl_b32 s101, s94, 8
	s_add_i32 s62, s62, s101
	v_or_b32_e32 v130, s62, v120
	s_lshl_b32 s50, s51, 4
	v_add_u32_e32 v16, s50, v130
	v_ashrrev_i32_e32 v17, 31, v16
	v_lshlrev_b64 v[16:17], 12, v[16:17]
	v_mov_b32_e32 v135, 0
	v_lshl_add_u64 v[118:119], v[96:97], 0, v[16:17]
	v_mov_b32_e32 v16, 0
	v_mov_b32_e32 v17, v135
	v_mov_b32_e32 v18, v135
	v_mov_b32_e32 v19, v135
	s_lshl_b32 s0, s99, 10
	s_mov_b32 s1, 0
	s_lshl_b32 s101, s99, 13
	v_add_u32_e32 v84, s101, v129
	v_lshl_add_u64 v[236:237], v[118:119], 0, s[0:1]
	s_cmp_lg_u32 s98, 0
	s_cbranch_scc1 .Lp5n_noload
	global_load_dwordx4 v[148:151], v[236:237], off offset:16
	global_load_dwordx4 v[152:155], v[236:237], off
	global_load_dwordx4 v[156:159], v[236:237], off offset:144
	global_load_dwordx4 v[160:163], v[236:237], off offset:128
	global_load_dwordx4 v[164:167], v[236:237], off offset:272
	global_load_dwordx4 v[168:171], v[236:237], off offset:256
	global_load_dwordx4 v[172:175], v[236:237], off offset:400
	global_load_dwordx4 v[176:179], v[236:237], off offset:384
	global_load_dwordx4 v[196:199], v[236:237], off offset:528
	global_load_dwordx4 v[200:203], v[236:237], off offset:512
	global_load_dwordx4 v[204:207], v[236:237], off offset:656
	global_load_dwordx4 v[208:211], v[236:237], off offset:640
	global_load_dwordx4 v[212:215], v[236:237], off offset:768
	global_load_dwordx4 v[216:219], v[236:237], off offset:784
	global_load_dwordx4 v[220:223], v[236:237], off offset:912
	global_load_dwordx4 v[224:227], v[236:237], off offset:896
.Lp5n_noload:
	v_add_u32_e32 v238, s50, v130
	v_ashrrev_i32_e32 v239, 31, v238
	v_lshlrev_b64 v[238:239], 11, v[238:239]
	v_lshl_add_u64 v[238:239], s[78:79], 0, v[238:239]
	v_lshl_add_u64 v[238:239], v[238:239], 0, v[240:241]
	s_waitcnt vmcnt(0)
	v_mov_b64_e32 v[80:81], v[148:149]
	v_mov_b64_e32 v[82:83], v[150:151]
	v_mov_b64_e32 v[136:137], v[152:153]
	v_mov_b64_e32 v[138:139], v[154:155]
	v_mov_b64_e32 v[68:69], v[156:157]
	v_mov_b64_e32 v[70:71], v[158:159]
	v_mov_b64_e32 v[72:73], v[160:161]
	v_mov_b64_e32 v[74:75], v[162:163]
	v_mov_b64_e32 v[60:61], v[164:165]
	v_mov_b64_e32 v[62:63], v[166:167]
	v_mov_b64_e32 v[64:65], v[168:169]
	v_mov_b64_e32 v[66:67], v[170:171]
	v_mov_b64_e32 v[52:53], v[172:173]
	v_mov_b64_e32 v[54:55], v[174:175]
	v_mov_b64_e32 v[56:57], v[176:177]
	v_mov_b64_e32 v[58:59], v[178:179]
	v_mov_b64_e32 v[44:45], v[196:197]
	v_mov_b64_e32 v[46:47], v[198:199]
	v_mov_b64_e32 v[48:49], v[200:201]
	v_mov_b64_e32 v[50:51], v[202:203]
	v_mov_b64_e32 v[36:37], v[204:205]
	v_mov_b64_e32 v[38:39], v[206:207]
	v_mov_b64_e32 v[40:41], v[208:209]
	v_mov_b64_e32 v[42:43], v[210:211]
	v_mov_b64_e32 v[32:33], v[212:213]
	v_mov_b64_e32 v[34:35], v[214:215]
	v_mov_b64_e32 v[28:29], v[216:217]
	v_mov_b64_e32 v[30:31], v[218:219]
	v_mov_b64_e32 v[20:21], v[220:221]
	v_mov_b64_e32 v[22:23], v[222:223]
	v_mov_b64_e32 v[24:25], v[224:225]
	v_mov_b64_e32 v[26:27], v[226:227]
	v_cvt_pk_bf16_f32 v78, v80, v81
	v_fmac_f32_e32 v135, v136, v136
	v_fmac_f32_e32 v135, v137, v137
	v_fmac_f32_e32 v135, v138, v138
	v_cvt_pk_bf16_f32 v76, v136, v137
	v_cvt_pk_bf16_f32 v77, v138, v139
	v_fmac_f32_e32 v135, v139, v139
	v_lshlrev_b32_e32 v140, 16, v76
	v_and_b32_e32 v141, 0xffff0000, v76
	v_lshlrev_b32_e32 v142, 16, v77
	v_and_b32_e32 v143, 0xffff0000, v77
	v_lshlrev_b32_e32 v144, 16, v78
	v_and_b32_e32 v145, 0xffff0000, v78
	v_sub_f32_e32 v140, v136, v140
	v_sub_f32_e32 v141, v137, v141
	v_sub_f32_e32 v142, v138, v142
	v_sub_f32_e32 v143, v139, v143
	v_fmac_f32_e32 v135, v80, v80
	v_sub_f32_e32 v144, v80, v144
	v_sub_f32_e32 v145, v81, v145
	v_fmac_f32_e32 v135, v81, v81
	v_cvt_pk_bf16_f32 v80, v140, v141
	v_cvt_pk_bf16_f32 v81, v142, v143
	ds_read_b128 v[136:139], v84
	ds_read_b128 v[140:143], v84 offset:32768
	v_cvt_pk_bf16_f32 v79, v82, v83
	v_fmac_f32_e32 v135, v82, v82
	s_waitcnt lgkmcnt(1)
	v_mfma_f32_16x16x32_bf16 v[16:19], v[76:79], v[136:139], v[16:19]
	v_lshlrev_b32_e32 v146, 16, v79
	v_and_b32_e32 v147, 0xffff0000, v79
	v_sub_f32_e32 v146, v82, v146
	v_sub_f32_e32 v147, v83, v147
	v_fmac_f32_e32 v135, v83, v83
	v_cvt_pk_bf16_f32 v82, v144, v145
	v_cvt_pk_bf16_f32 v83, v146, v147
	v_fmac_f32_e32 v135, v72, v72
	v_mfma_f32_16x16x32_bf16 v[16:19], v[80:83], v[136:139], v[16:19]
	v_fmac_f32_e32 v135, v73, v73
	v_fmac_f32_e32 v135, v74, v74
	v_fmac_f32_e32 v135, v75, v75
	s_waitcnt lgkmcnt(0)
	v_mfma_f32_16x16x32_bf16 v[16:19], v[76:79], v[140:143], v[16:19]
	v_cvt_pk_bf16_f32 v76, v72, v73
	v_cvt_pk_bf16_f32 v77, v74, v75
	v_cvt_pk_bf16_f32 v78, v68, v69
	v_fmac_f32_e32 v135, v68, v68
	v_lshlrev_b32_e32 v80, 16, v76
	v_and_b32_e32 v81, 0xffff0000, v76
	v_lshlrev_b32_e32 v82, 16, v77
	v_and_b32_e32 v83, 0xffff0000, v77
	v_lshlrev_b32_e32 v136, 16, v78
	v_and_b32_e32 v137, 0xffff0000, v78
	v_sub_f32_e32 v80, v72, v80
	v_sub_f32_e32 v81, v73, v81
	v_sub_f32_e32 v82, v74, v82
	v_sub_f32_e32 v83, v75, v83
	v_sub_f32_e32 v136, v68, v136
	v_sub_f32_e32 v137, v69, v137
	v_fmac_f32_e32 v135, v69, v69
	v_cvt_pk_bf16_f32 v68, v80, v81
	v_cvt_pk_bf16_f32 v69, v82, v83
	ds_read_b128 v[72:75], v84 offset:1024
	ds_read_b128 v[80:83], v84 offset:33792
	v_cvt_pk_bf16_f32 v79, v70, v71
	v_fmac_f32_e32 v135, v70, v70
	s_waitcnt lgkmcnt(1)
	v_mfma_f32_16x16x32_bf16 v[16:19], v[76:79], v[72:75], v[16:19]
	v_lshlrev_b32_e32 v138, 16, v79
	v_and_b32_e32 v139, 0xffff0000, v79
	v_fmac_f32_e32 v135, v71, v71
	v_sub_f32_e32 v138, v70, v138
	v_sub_f32_e32 v139, v71, v139
	v_cvt_pk_bf16_f32 v70, v136, v137
	v_cvt_pk_bf16_f32 v71, v138, v139
	v_fmac_f32_e32 v135, v64, v64
	v_mfma_f32_16x16x32_bf16 v[16:19], v[68:71], v[72:75], v[16:19]
	v_fmac_f32_e32 v135, v65, v65
	v_fmac_f32_e32 v135, v66, v66
	v_cvt_pk_bf16_f32 v68, v64, v65
	v_cvt_pk_bf16_f32 v69, v66, v67
	v_fmac_f32_e32 v135, v67, v67
	v_lshlrev_b32_e32 v72, 16, v68
	v_and_b32_e32 v73, 0xffff0000, v68
	v_lshlrev_b32_e32 v74, 16, v69
	v_and_b32_e32 v75, 0xffff0000, v69
	s_waitcnt lgkmcnt(0)
	v_mfma_f32_16x16x32_bf16 v[16:19], v[76:79], v[80:83], v[16:19]
	v_cvt_pk_bf16_f32 v70, v60, v61
	v_sub_f32_e32 v72, v64, v72
	v_lshlrev_b32_e32 v76, 16, v70
	v_and_b32_e32 v77, 0xffff0000, v70
	v_sub_f32_e32 v73, v65, v73
	v_sub_f32_e32 v74, v66, v74
	v_sub_f32_e32 v75, v67, v75
	v_fmac_f32_e32 v135, v60, v60
	v_sub_f32_e32 v76, v60, v76
	v_sub_f32_e32 v77, v61, v77
	v_fmac_f32_e32 v135, v61, v61
	v_cvt_pk_bf16_f32 v60, v72, v73
	v_cvt_pk_bf16_f32 v61, v74, v75
	ds_read_b128 v[64:67], v84 offset:2048
	ds_read_b128 v[72:75], v84 offset:34816
	v_cvt_pk_bf16_f32 v71, v62, v63
	v_fmac_f32_e32 v135, v62, v62
	s_waitcnt lgkmcnt(1)
	v_mfma_f32_16x16x32_bf16 v[16:19], v[68:71], v[64:67], v[16:19]
	v_lshlrev_b32_e32 v78, 16, v71
	v_and_b32_e32 v79, 0xffff0000, v71
	v_fmac_f32_e32 v135, v63, v63
	v_sub_f32_e32 v78, v62, v78
	v_sub_f32_e32 v79, v63, v79
	v_cvt_pk_bf16_f32 v62, v76, v77
	v_cvt_pk_bf16_f32 v63, v78, v79
	v_fmac_f32_e32 v135, v56, v56
	v_mfma_f32_16x16x32_bf16 v[16:19], v[60:63], v[64:67], v[16:19]
	v_fmac_f32_e32 v135, v57, v57
	v_fmac_f32_e32 v135, v58, v58
	v_cvt_pk_bf16_f32 v60, v56, v57
	v_cvt_pk_bf16_f32 v61, v58, v59
	v_fmac_f32_e32 v135, v59, v59
	v_lshlrev_b32_e32 v64, 16, v60
	v_and_b32_e32 v65, 0xffff0000, v60
	v_lshlrev_b32_e32 v66, 16, v61
	v_and_b32_e32 v67, 0xffff0000, v61
	s_waitcnt lgkmcnt(0)
	v_mfma_f32_16x16x32_bf16 v[16:19], v[68:71], v[72:75], v[16:19]
	v_cvt_pk_bf16_f32 v62, v52, v53
	v_sub_f32_e32 v64, v56, v64
	v_lshlrev_b32_e32 v68, 16, v62
	v_and_b32_e32 v69, 0xffff0000, v62
	v_sub_f32_e32 v65, v57, v65
	v_sub_f32_e32 v66, v58, v66
	v_sub_f32_e32 v67, v59, v67
	v_fmac_f32_e32 v135, v52, v52
	v_sub_f32_e32 v68, v52, v68
	v_sub_f32_e32 v69, v53, v69
	v_fmac_f32_e32 v135, v53, v53
	v_cvt_pk_bf16_f32 v52, v64, v65
	v_cvt_pk_bf16_f32 v53, v66, v67
	ds_read_b128 v[56:59], v84 offset:3072
	ds_read_b128 v[64:67], v84 offset:35840
	v_cvt_pk_bf16_f32 v63, v54, v55
	v_fmac_f32_e32 v135, v54, v54
	s_waitcnt lgkmcnt(1)
	v_mfma_f32_16x16x32_bf16 v[16:19], v[60:63], v[56:59], v[16:19]
	v_lshlrev_b32_e32 v70, 16, v63
	v_and_b32_e32 v71, 0xffff0000, v63
	v_fmac_f32_e32 v135, v55, v55
	v_sub_f32_e32 v70, v54, v70
	v_sub_f32_e32 v71, v55, v71
	v_cvt_pk_bf16_f32 v54, v68, v69
	v_cvt_pk_bf16_f32 v55, v70, v71
	v_fmac_f32_e32 v135, v48, v48
	v_mfma_f32_16x16x32_bf16 v[16:19], v[52:55], v[56:59], v[16:19]
	v_fmac_f32_e32 v135, v49, v49
	v_fmac_f32_e32 v135, v50, v50
	v_cvt_pk_bf16_f32 v52, v48, v49
	v_cvt_pk_bf16_f32 v53, v50, v51
	v_fmac_f32_e32 v135, v51, v51
	v_lshlrev_b32_e32 v56, 16, v52
	v_and_b32_e32 v57, 0xffff0000, v52
	v_lshlrev_b32_e32 v58, 16, v53
	v_and_b32_e32 v59, 0xffff0000, v53
	s_waitcnt lgkmcnt(0)
	v_mfma_f32_16x16x32_bf16 v[16:19], v[60:63], v[64:67], v[16:19]
	v_cvt_pk_bf16_f32 v54, v44, v45
	v_sub_f32_e32 v56, v48, v56
	v_lshlrev_b32_e32 v60, 16, v54
	v_and_b32_e32 v61, 0xffff0000, v54
	v_sub_f32_e32 v57, v49, v57
	v_sub_f32_e32 v58, v50, v58
	v_sub_f32_e32 v59, v51, v59
	v_fmac_f32_e32 v135, v44, v44
	v_sub_f32_e32 v60, v44, v60
	v_sub_f32_e32 v61, v45, v61
	v_fmac_f32_e32 v135, v45, v45
	v_cvt_pk_bf16_f32 v44, v56, v57
	v_cvt_pk_bf16_f32 v45, v58, v59
	ds_read_b128 v[48:51], v84 offset:4096
	ds_read_b128 v[56:59], v84 offset:36864
	v_cvt_pk_bf16_f32 v55, v46, v47
	v_fmac_f32_e32 v135, v46, v46
	s_waitcnt lgkmcnt(1)
	v_mfma_f32_16x16x32_bf16 v[16:19], v[52:55], v[48:51], v[16:19]
	v_lshlrev_b32_e32 v62, 16, v55
	v_and_b32_e32 v63, 0xffff0000, v55
	v_fmac_f32_e32 v135, v47, v47
	v_sub_f32_e32 v62, v46, v62
	v_sub_f32_e32 v63, v47, v63
	v_cvt_pk_bf16_f32 v46, v60, v61
	v_cvt_pk_bf16_f32 v47, v62, v63
	v_fmac_f32_e32 v135, v40, v40
	v_mfma_f32_16x16x32_bf16 v[16:19], v[44:47], v[48:51], v[16:19]
	v_fmac_f32_e32 v135, v41, v41
	v_fmac_f32_e32 v135, v42, v42
	v_cvt_pk_bf16_f32 v44, v40, v41
	v_cvt_pk_bf16_f32 v45, v42, v43
	v_fmac_f32_e32 v135, v43, v43
	v_lshlrev_b32_e32 v48, 16, v44
	v_and_b32_e32 v49, 0xffff0000, v44
	v_lshlrev_b32_e32 v50, 16, v45
	v_and_b32_e32 v51, 0xffff0000, v45
	s_waitcnt lgkmcnt(0)
	v_mfma_f32_16x16x32_bf16 v[16:19], v[52:55], v[56:59], v[16:19]
	v_cvt_pk_bf16_f32 v46, v36, v37
	v_sub_f32_e32 v48, v40, v48
	v_lshlrev_b32_e32 v52, 16, v46
	v_and_b32_e32 v53, 0xffff0000, v46
	v_sub_f32_e32 v49, v41, v49
	v_sub_f32_e32 v50, v42, v50
	v_sub_f32_e32 v51, v43, v51
	v_fmac_f32_e32 v135, v36, v36
	v_sub_f32_e32 v52, v36, v52
	v_sub_f32_e32 v53, v37, v53
	v_fmac_f32_e32 v135, v37, v37
	v_cvt_pk_bf16_f32 v36, v48, v49
	v_cvt_pk_bf16_f32 v37, v50, v51
	ds_read_b128 v[40:43], v84 offset:5120
	ds_read_b128 v[48:51], v84 offset:37888
	v_cvt_pk_bf16_f32 v47, v38, v39
	v_fmac_f32_e32 v135, v38, v38
	s_waitcnt lgkmcnt(1)
	v_mfma_f32_16x16x32_bf16 v[16:19], v[44:47], v[40:43], v[16:19]
	v_lshlrev_b32_e32 v54, 16, v47
	v_and_b32_e32 v55, 0xffff0000, v47
	v_sub_f32_e32 v54, v38, v54
	v_sub_f32_e32 v55, v39, v55
	v_fmac_f32_e32 v135, v39, v39
	v_cvt_pk_bf16_f32 v38, v52, v53
	v_cvt_pk_bf16_f32 v39, v54, v55
	v_fmac_f32_e32 v135, v32, v32
	v_mfma_f32_16x16x32_bf16 v[16:19], v[36:39], v[40:43], v[16:19]
	v_mov_b32_e32 v36, v28
	v_mov_b32_e32 v37, v35
	v_pk_mul_f32 v[42:43], v[30:31], v[30:31]
	v_fmac_f32_e32 v135, v33, v33
	v_pk_mul_f32 v[40:41], v[36:37], v[36:37]
	v_cvt_pk_bf16_f32 v36, v32, v33
	v_fmac_f32_e32 v135, v34, v34
	v_lshlrev_b32_e32 v43, 16, v36
	s_waitcnt lgkmcnt(0)
	v_mfma_f32_16x16x32_bf16 v[16:19], v[44:47], v[48:51], v[16:19]
	v_mul_f32_e64 v44, v28, v28
	v_mul_f32_e64 v45, v29, v29
	v_sub_f32_e32 v43, v32, v43
	v_add_f32_e32 v32, v41, v135
	v_cvt_pk_bf16_f32 v37, v34, v35
	v_cvt_pk_bf16_f32 v39, v30, v31
	v_and_b32_e32 v44, 0xffff0000, v36
	v_lshlrev_b32_e32 v46, 16, v37
	v_and_b32_e32 v47, 0xffff0000, v37
	v_and_b32_e32 v51, 0xffff0000, v39
	v_add_f32_e32 v32, v40, v32
	v_cvt_pk_bf16_f32 v38, v28, v29
	v_lshlrev_b32_e32 v50, 16, v39
	v_lshlrev_b32_e32 v48, 16, v38
	v_sub_f32_e32 v44, v33, v44
	v_sub_f32_e32 v46, v34, v46
	v_sub_f32_e32 v35, v35, v47
	v_sub_f32_e32 v47, v31, v51
	v_add_f32_e32 v32, v45, v32
	v_sub_f32_e32 v28, v28, v48
	v_sub_f32_e32 v30, v30, v50
	v_add_f32_e32 v48, v42, v32
	v_cvt_pk_bf16_f32 v32, v43, v44
	v_cvt_pk_bf16_f32 v33, v46, v35
	v_cvt_pk_bf16_f32 v35, v30, v47
	ds_read_b128 v[40:43], v84 offset:6144
	ds_read_b128 v[44:47], v84 offset:38912
	s_waitcnt lgkmcnt(1)
	v_mfma_f32_16x16x32_bf16 v[16:19], v[36:39], v[40:43], v[16:19]
	v_and_b32_e32 v49, 0xffff0000, v38
	v_sub_f32_e32 v29, v29, v49
	v_cvt_pk_bf16_f32 v34, v28, v29
	v_mov_b32_e32 v30, v24
	v_mfma_f32_16x16x32_bf16 v[16:19], v[32:35], v[40:43], v[16:19]
	v_mul_f32_e64 v32, v30, v30
	v_mul_f32_e64 v33, v31, v31
	v_pk_mul_f32 v[34:35], v[26:27], v[26:27]
	v_mov_b32_e32 v28, v20
	v_mov_b32_e32 v29, v27
	s_waitcnt lgkmcnt(0)
	v_mfma_f32_16x16x32_bf16 v[16:19], v[36:39], v[44:47], v[16:19]
	v_add_f32_e32 v33, v33, v48
	v_pk_mul_f32 v[38:39], v[28:29], v[28:29]
	v_cvt_pk_bf16_f32 v28, v24, v25
	v_cvt_pk_bf16_f32 v30, v20, v21
	v_pk_mul_f32 v[36:37], v[24:25], v[24:25]
	v_lshlrev_b32_e32 v35, 16, v28
	v_lshlrev_b32_e32 v44, 16, v30
	v_pk_mul_f32 v[42:43], v[20:21], v[20:21]
	v_sub_f32_e32 v24, v24, v35
	v_sub_f32_e32 v35, v20, v44
	v_add_f32_e32 v20, v32, v33
	v_add_f32_e32 v20, v37, v20
	v_add_f32_e32 v20, v34, v20
	v_pk_mul_f32 v[40:41], v[22:23], v[22:23]
	v_add_f32_e32 v20, v39, v20
	v_cvt_pk_bf16_f32 v29, v26, v27
	v_and_b32_e32 v36, 0xffff0000, v28
	v_lshlrev_b32_e32 v41, 16, v29
	v_and_b32_e32 v42, 0xffff0000, v29
	v_add_f32_e32 v20, v38, v20
	v_cvt_pk_bf16_f32 v31, v22, v23
	v_and_b32_e32 v45, 0xffff0000, v30
	v_lshlrev_b32_e32 v46, 16, v31
	v_sub_f32_e32 v25, v25, v36
	v_sub_f32_e32 v26, v26, v41
	v_sub_f32_e32 v27, v27, v42
	v_add_f32_e32 v20, v43, v20
	v_sub_f32_e32 v36, v21, v45
	v_sub_f32_e32 v41, v22, v46
	v_add_f32_e32 v135, v40, v20
	v_cvt_pk_bf16_f32 v20, v24, v25
	v_cvt_pk_bf16_f32 v21, v26, v27
	v_cvt_pk_bf16_f32 v22, v35, v36
	ds_read_b128 v[24:27], v84 offset:7168
	ds_read_b128 v[32:35], v84 offset:39936
	s_waitcnt lgkmcnt(1)
	v_mfma_f32_16x16x32_bf16 v[16:19], v[28:31], v[24:27], v[16:19]
	v_and_b32_e32 v47, 0xffff0000, v31
	v_sub_f32_e32 v42, v23, v47
	v_fmac_f32_e32 v135, v23, v23
	v_cvt_pk_bf16_f32 v23, v41, v42
	v_add_u32_e32 v84, 0x2000, v84
	v_mfma_f32_16x16x32_bf16 v[16:19], v[20:23], v[24:27], v[16:19]
	s_waitcnt lgkmcnt(0)
	v_mfma_f32_16x16x32_bf16 v[16:19], v[28:31], v[32:35], v[16:19]
	s_nop 7
	s_nop 7
	ds_write_b128 v231, v[16:19]
	ds_write_b32 v232, v135
	s_waitcnt lgkmcnt(0)
	s_barrier
	ds_read_b128 v[16:19], v233
	ds_read_b128 v[20:23], v233 offset:1280
	ds_read_b128 v[24:27], v233 offset:2560
	ds_read_b128 v[28:31], v233 offset:3840
	ds_read_b32 v135, v234
	ds_read_b32 v32, v234 offset:1280
	ds_read_b32 v33, v234 offset:2560
	ds_read_b32 v34, v234 offset:3840
	s_waitcnt lgkmcnt(0)
	v_pk_add_f32 v[16:17], v[16:17], v[20:21]
	v_pk_add_f32 v[18:19], v[18:19], v[22:23]
	v_pk_add_f32 v[16:17], v[16:17], v[24:25]
	v_pk_add_f32 v[18:19], v[18:19], v[26:27]
	v_pk_add_f32 v[16:17], v[16:17], v[28:29]
	v_pk_add_f32 v[18:19], v[18:19], v[30:31]
	v_add_f32_e32 v135, v135, v32
	v_add_f32_e32 v135, v135, v33
	v_add_f32_e32 v135, v135, v34
	v_and_b32_e32 v24, 64, v133
	v_xor_b32_e32 v20, 16, v133
	v_add_u32_e32 v21, 64, v24
	v_cmp_lt_i32_e32 vcc, v20, v21
	v_xor_b32_e32 v22, 32, v133
	s_mov_b32 s0, 0x800000
	v_cndmask_b32_e32 v20, v133, v20, vcc
	v_lshlrev_b32_e32 v20, 2, v20
	ds_bpermute_b32 v20, v20, v135
	v_cmp_lt_i32_e32 vcc, v22, v21
	v_or_b32_e32 v25, v24, v122
	v_lshlrev_b32_e32 v25, 2, v25
	v_cndmask_b32_e32 v22, v133, v22, vcc
	s_waitcnt lgkmcnt(0)
	v_add_f32_e32 v20, v135, v20
	v_lshlrev_b32_e32 v22, 2, v22
	ds_bpermute_b32 v22, v22, v20
	v_xor_b32_e32 v23, 1, v133
	v_or_b32_e32 v28, v24, v123
	s_add_i32 s84, s62, s50
	s_mov_b32 s85, -4
	s_waitcnt lgkmcnt(0)
	v_add_f32_e32 v20, v20, v22
	v_fmamk_f32 v20, v20, 0x3a800000, v132
	v_mul_f32_e32 v22, 0x4b800000, v20
	v_cmp_gt_f32_e32 vcc, s0, v20
	s_or_b32 s0, s51, s61
	s_lshl_b32 s0, s0, 4
	v_cndmask_b32_e32 v20, v20, v22, vcc
	v_rsq_f32_e32 v20, v20
	v_xor_b32_e32 v22, 2, v133
	s_add_i32 s0, s0, s33
	s_and_b32 s0, s0, 0xff0
	v_mul_f32_e32 v26, 0x45800000, v20
	v_cndmask_b32_e32 v64, v20, v26, vcc
	s_cmp_eq_u32 s98, 7
	s_cbranch_scc1 .Lp5n_last
	v_add_co_u32_e32 v228, vcc, 0x10000, v236
	v_addc_co_u32_e32 v229, vcc, 0, v237, vcc
	ds_read_b128 v[242:245], v230 offset:0
	ds_read_b128 v[246:249], v230 offset:16
	ds_read_b128 v[250:253], v230 offset:4096
	ds_read_b128 v[180:183], v230 offset:4112
	s_waitcnt lgkmcnt(0)
	v_pk_mul_f32 v[184:185], v[152:153], v[64:65] op_sel_hi:[1,0]
	v_pk_mul_f32 v[186:187], v[154:155], v[64:65] op_sel_hi:[1,0]
	v_pk_mul_f32 v[188:189], v[148:149], v[64:65] op_sel_hi:[1,0]
	v_pk_mul_f32 v[190:191], v[150:151], v[64:65] op_sel_hi:[1,0]
	v_pk_fma_f32 v[184:185], v[242:243], v[184:185], v[250:251]
	v_pk_fma_f32 v[186:187], v[244:245], v[186:187], v[252:253]
	v_pk_fma_f32 v[188:189], v[246:247], v[188:189], v[180:181]
	v_pk_fma_f32 v[190:191], v[248:249], v[190:191], v[182:183]
	ds_read_b128 v[242:245], v230 offset:128
	ds_read_b128 v[246:249], v230 offset:144
	ds_read_b128 v[250:253], v230 offset:4224
	ds_read_b128 v[180:183], v230 offset:4240
	v_cvt_pk_bf16_f32 v184, v184, v185
	v_cvt_pk_bf16_f32 v185, v186, v187
	v_cvt_pk_bf16_f32 v186, v188, v189
	v_cvt_pk_bf16_f32 v187, v190, v191
	global_store_dwordx4 v[238:239], v[184:187], off offset:0
	global_load_dwordx4 v[152:155], v[228:229], off offset:0
	global_load_dwordx4 v[148:151], v[228:229], off offset:16
	s_waitcnt lgkmcnt(0)
	v_pk_mul_f32 v[184:185], v[160:161], v[64:65] op_sel_hi:[1,0]
	v_pk_mul_f32 v[186:187], v[162:163], v[64:65] op_sel_hi:[1,0]
	v_pk_mul_f32 v[188:189], v[156:157], v[64:65] op_sel_hi:[1,0]
	v_pk_mul_f32 v[190:191], v[158:159], v[64:65] op_sel_hi:[1,0]
	v_pk_fma_f32 v[184:185], v[242:243], v[184:185], v[250:251]
	v_pk_fma_f32 v[186:187], v[244:245], v[186:187], v[252:253]
	v_pk_fma_f32 v[188:189], v[246:247], v[188:189], v[180:181]
	v_pk_fma_f32 v[190:191], v[248:249], v[190:191], v[182:183]
	ds_read_b128 v[242:245], v230 offset:256
	ds_read_b128 v[246:249], v230 offset:272
	ds_read_b128 v[250:253], v230 offset:4352
	ds_read_b128 v[180:183], v230 offset:4368
	v_cvt_pk_bf16_f32 v184, v184, v185
	v_cvt_pk_bf16_f32 v185, v186, v187
	v_cvt_pk_bf16_f32 v186, v188, v189
	v_cvt_pk_bf16_f32 v187, v190, v191
	global_store_dwordx4 v[238:239], v[184:187], off offset:64
	global_load_dwordx4 v[160:163], v[228:229], off offset:128
	global_load_dwordx4 v[156:159], v[228:229], off offset:144
	s_waitcnt lgkmcnt(0)
	v_pk_mul_f32 v[184:185], v[168:169], v[64:65] op_sel_hi:[1,0]
	v_pk_mul_f32 v[186:187], v[170:171], v[64:65] op_sel_hi:[1,0]
	v_pk_mul_f32 v[188:189], v[164:165], v[64:65] op_sel_hi:[1,0]
	v_pk_mul_f32 v[190:191], v[166:167], v[64:65] op_sel_hi:[1,0]
	v_pk_fma_f32 v[184:185], v[242:243], v[184:185], v[250:251]
	v_pk_fma_f32 v[186:187], v[244:245], v[186:187], v[252:253]
	v_pk_fma_f32 v[188:189], v[246:247], v[188:189], v[180:181]
	v_pk_fma_f32 v[190:191], v[248:249], v[190:191], v[182:183]
	ds_read_b128 v[242:245], v230 offset:384
	ds_read_b128 v[246:249], v230 offset:400
	ds_read_b128 v[250:253], v230 offset:4480
	ds_read_b128 v[180:183], v230 offset:4496
	v_cvt_pk_bf16_f32 v184, v184, v185
	v_cvt_pk_bf16_f32 v185, v186, v187
	v_cvt_pk_bf16_f32 v186, v188, v189
	v_cvt_pk_bf16_f32 v187, v190, v191
	global_store_dwordx4 v[238:239], v[184:187], off offset:128
	global_load_dwordx4 v[168:171], v[228:229], off offset:256
	global_load_dwordx4 v[164:167], v[228:229], off offset:272
	s_waitcnt lgkmcnt(0)
	v_pk_mul_f32 v[184:185], v[176:177], v[64:65] op_sel_hi:[1,0]
	v_pk_mul_f32 v[186:187], v[178:179], v[64:65] op_sel_hi:[1,0]
	v_pk_mul_f32 v[188:189], v[172:173], v[64:65] op_sel_hi:[1,0]
	v_pk_mul_f32 v[190:191], v[174:175], v[64:65] op_sel_hi:[1,0]
	v_pk_fma_f32 v[184:185], v[242:243], v[184:185], v[250:251]
	v_pk_fma_f32 v[186:187], v[244:245], v[186:187], v[252:253]
	v_pk_fma_f32 v[188:189], v[246:247], v[188:189], v[180:181]
	v_pk_fma_f32 v[190:191], v[248:249], v[190:191], v[182:183]
	ds_read_b128 v[242:245], v230 offset:512
	ds_read_b128 v[246:249], v230 offset:528
	ds_read_b128 v[250:253], v230 offset:4608
	ds_read_b128 v[180:183], v230 offset:4624
	v_cvt_pk_bf16_f32 v184, v184, v185
	v_cvt_pk_bf16_f32 v185, v186, v187
	v_cvt_pk_bf16_f32 v186, v188, v189
	v_cvt_pk_bf16_f32 v187, v190, v191
	global_store_dwordx4 v[238:239], v[184:187], off offset:192
	global_load_dwordx4 v[176:179], v[228:229], off offset:384
	global_load_dwordx4 v[172:175], v[228:229], off offset:400
	s_waitcnt lgkmcnt(0)
	v_pk_mul_f32 v[184:185], v[200:201], v[64:65] op_sel_hi:[1,0]
	v_pk_mul_f32 v[186:187], v[202:203], v[64:65] op_sel_hi:[1,0]
	v_pk_mul_f32 v[188:189], v[196:197], v[64:65] op_sel_hi:[1,0]
	v_pk_mul_f32 v[190:191], v[198:199], v[64:65] op_sel_hi:[1,0]
	v_pk_fma_f32 v[184:185], v[242:243], v[184:185], v[250:251]
	v_pk_fma_f32 v[186:187], v[244:245], v[186:187], v[252:253]
	v_pk_fma_f32 v[188:189], v[246:247], v[188:189], v[180:181]
	v_pk_fma_f32 v[190:191], v[248:249], v[190:191], v[182:183]
	ds_read_b128 v[242:245], v230 offset:640
	ds_read_b128 v[246:249], v230 offset:656
	ds_read_b128 v[250:253], v230 offset:4736
	ds_read_b128 v[180:183], v230 offset:4752
	v_cvt_pk_bf16_f32 v184, v184, v185
	v_cvt_pk_bf16_f32 v185, v186, v187
	v_cvt_pk_bf16_f32 v186, v188, v189
	v_cvt_pk_bf16_f32 v187, v190, v191
	global_store_dwordx4 v[238:239], v[184:187], off offset:256
	global_load_dwordx4 v[200:203], v[228:229], off offset:512
	global_load_dwordx4 v[196:199], v[228:229], off offset:528
	s_waitcnt lgkmcnt(0)
	v_pk_mul_f32 v[184:185], v[208:209], v[64:65] op_sel_hi:[1,0]
	v_pk_mul_f32 v[186:187], v[210:211], v[64:65] op_sel_hi:[1,0]
	v_pk_mul_f32 v[188:189], v[204:205], v[64:65] op_sel_hi:[1,0]
	v_pk_mul_f32 v[190:191], v[206:207], v[64:65] op_sel_hi:[1,0]
	v_pk_fma_f32 v[184:185], v[242:243], v[184:185], v[250:251]
	v_pk_fma_f32 v[186:187], v[244:245], v[186:187], v[252:253]
	v_pk_fma_f32 v[188:189], v[246:247], v[188:189], v[180:181]
	v_pk_fma_f32 v[190:191], v[248:249], v[190:191], v[182:183]
	ds_read_b128 v[242:245], v230 offset:768
	ds_read_b128 v[246:249], v230 offset:784
	ds_read_b128 v[250:253], v230 offset:4864
	ds_read_b128 v[180:183], v230 offset:4880
	v_cvt_pk_bf16_f32 v184, v184, v185
	v_cvt_pk_bf16_f32 v185, v186, v187
	v_cvt_pk_bf16_f32 v186, v188, v189
	v_cvt_pk_bf16_f32 v187, v190, v191
	global_store_dwordx4 v[238:239], v[184:187], off offset:320
	global_load_dwordx4 v[208:211], v[228:229], off offset:640
	global_load_dwordx4 v[204:207], v[228:229], off offset:656
	s_waitcnt lgkmcnt(0)
	v_pk_mul_f32 v[184:185], v[212:213], v[64:65] op_sel_hi:[1,0]
	v_pk_mul_f32 v[186:187], v[214:215], v[64:65] op_sel_hi:[1,0]
	v_pk_mul_f32 v[188:189], v[216:217], v[64:65] op_sel_hi:[1,0]
	v_pk_mul_f32 v[190:191], v[218:219], v[64:65] op_sel_hi:[1,0]
	v_pk_fma_f32 v[184:185], v[242:243], v[184:185], v[250:251]
	v_pk_fma_f32 v[186:187], v[244:245], v[186:187], v[252:253]
	v_pk_fma_f32 v[188:189], v[246:247], v[188:189], v[180:181]
	v_pk_fma_f32 v[190:191], v[248:249], v[190:191], v[182:183]
	ds_read_b128 v[242:245], v230 offset:896
	ds_read_b128 v[246:249], v230 offset:912
	ds_read_b128 v[250:253], v230 offset:4992
	ds_read_b128 v[180:183], v230 offset:5008
	v_cvt_pk_bf16_f32 v184, v184, v185
	v_cvt_pk_bf16_f32 v185, v186, v187
	v_cvt_pk_bf16_f32 v186, v188, v189
	v_cvt_pk_bf16_f32 v187, v190, v191
	global_store_dwordx4 v[238:239], v[184:187], off offset:384
	global_load_dwordx4 v[212:215], v[228:229], off offset:768
	global_load_dwordx4 v[216:219], v[228:229], off offset:784
	s_waitcnt lgkmcnt(0)
	v_pk_mul_f32 v[184:185], v[224:225], v[64:65] op_sel_hi:[1,0]
	v_pk_mul_f32 v[186:187], v[226:227], v[64:65] op_sel_hi:[1,0]
	v_pk_mul_f32 v[188:189], v[220:221], v[64:65] op_sel_hi:[1,0]
	v_pk_mul_f32 v[190:191], v[222:223], v[64:65] op_sel_hi:[1,0]
	v_pk_fma_f32 v[184:185], v[242:243], v[184:185], v[250:251]
	v_pk_fma_f32 v[186:187], v[244:245], v[186:187], v[252:253]
	v_pk_fma_f32 v[188:189], v[246:247], v[188:189], v[180:181]
	v_pk_fma_f32 v[190:191], v[248:249], v[190:191], v[182:183]
	v_cvt_pk_bf16_f32 v184, v184, v185
	v_cvt_pk_bf16_f32 v185, v186, v187
	v_cvt_pk_bf16_f32 v186, v188, v189
	v_cvt_pk_bf16_f32 v187, v190, v191
	global_store_dwordx4 v[238:239], v[184:187], off offset:448
	global_load_dwordx4 v[224:227], v[228:229], off offset:896
	global_load_dwordx4 v[220:223], v[228:229], off offset:912
	s_branch .Lp5n_c2
.Lp5n_last:
	ds_read_b128 v[242:245], v230 offset:0
	ds_read_b128 v[246:249], v230 offset:16
	ds_read_b128 v[250:253], v230 offset:4096
	ds_read_b128 v[180:183], v230 offset:4112
	s_waitcnt lgkmcnt(0)
	v_pk_mul_f32 v[184:185], v[152:153], v[64:65] op_sel_hi:[1,0]
	v_pk_mul_f32 v[186:187], v[154:155], v[64:65] op_sel_hi:[1,0]
	v_pk_mul_f32 v[188:189], v[148:149], v[64:65] op_sel_hi:[1,0]
	v_pk_mul_f32 v[190:191], v[150:151], v[64:65] op_sel_hi:[1,0]
	v_pk_fma_f32 v[184:185], v[242:243], v[184:185], v[250:251]
	v_pk_fma_f32 v[186:187], v[244:245], v[186:187], v[252:253]
	v_pk_fma_f32 v[188:189], v[246:247], v[188:189], v[180:181]
	v_pk_fma_f32 v[190:191], v[248:249], v[190:191], v[182:183]
	ds_read_b128 v[242:245], v230 offset:128
	ds_read_b128 v[246:249], v230 offset:144
	ds_read_b128 v[250:253], v230 offset:4224
	ds_read_b128 v[180:183], v230 offset:4240
	v_cvt_pk_bf16_f32 v184, v184, v185
	v_cvt_pk_bf16_f32 v185, v186, v187
	v_cvt_pk_bf16_f32 v186, v188, v189
	v_cvt_pk_bf16_f32 v187, v190, v191
	global_store_dwordx4 v[238:239], v[184:187], off offset:0
	s_nop 0
	s_waitcnt lgkmcnt(0)
	v_pk_mul_f32 v[184:185], v[160:161], v[64:65] op_sel_hi:[1,0]
	v_pk_mul_f32 v[186:187], v[162:163], v[64:65] op_sel_hi:[1,0]
	v_pk_mul_f32 v[188:189], v[156:157], v[64:65] op_sel_hi:[1,0]
	v_pk_mul_f32 v[190:191], v[158:159], v[64:65] op_sel_hi:[1,0]
	v_pk_fma_f32 v[184:185], v[242:243], v[184:185], v[250:251]
	v_pk_fma_f32 v[186:187], v[244:245], v[186:187], v[252:253]
	v_pk_fma_f32 v[188:189], v[246:247], v[188:189], v[180:181]
	v_pk_fma_f32 v[190:191], v[248:249], v[190:191], v[182:183]
	ds_read_b128 v[242:245], v230 offset:256
	ds_read_b128 v[246:249], v230 offset:272
	ds_read_b128 v[250:253], v230 offset:4352
	ds_read_b128 v[180:183], v230 offset:4368
	v_cvt_pk_bf16_f32 v184, v184, v185
	v_cvt_pk_bf16_f32 v185, v186, v187
	v_cvt_pk_bf16_f32 v186, v188, v189
	v_cvt_pk_bf16_f32 v187, v190, v191
	global_store_dwordx4 v[238:239], v[184:187], off offset:64
	s_nop 0
	s_waitcnt lgkmcnt(0)
	v_pk_mul_f32 v[184:185], v[168:169], v[64:65] op_sel_hi:[1,0]
	v_pk_mul_f32 v[186:187], v[170:171], v[64:65] op_sel_hi:[1,0]
	v_pk_mul_f32 v[188:189], v[164:165], v[64:65] op_sel_hi:[1,0]
	v_pk_mul_f32 v[190:191], v[166:167], v[64:65] op_sel_hi:[1,0]
	v_pk_fma_f32 v[184:185], v[242:243], v[184:185], v[250:251]
	v_pk_fma_f32 v[186:187], v[244:245], v[186:187], v[252:253]
	v_pk_fma_f32 v[188:189], v[246:247], v[188:189], v[180:181]
	v_pk_fma_f32 v[190:191], v[248:249], v[190:191], v[182:183]
	ds_read_b128 v[242:245], v230 offset:384
	ds_read_b128 v[246:249], v230 offset:400
	ds_read_b128 v[250:253], v230 offset:4480
	ds_read_b128 v[180:183], v230 offset:4496
	v_cvt_pk_bf16_f32 v184, v184, v185
	v_cvt_pk_bf16_f32 v185, v186, v187
	v_cvt_pk_bf16_f32 v186, v188, v189
	v_cvt_pk_bf16_f32 v187, v190, v191
	global_store_dwordx4 v[238:239], v[184:187], off offset:128
	s_nop 0
	s_waitcnt lgkmcnt(0)
	v_pk_mul_f32 v[184:185], v[176:177], v[64:65] op_sel_hi:[1,0]
	v_pk_mul_f32 v[186:187], v[178:179], v[64:65] op_sel_hi:[1,0]
	v_pk_mul_f32 v[188:189], v[172:173], v[64:65] op_sel_hi:[1,0]
	v_pk_mul_f32 v[190:191], v[174:175], v[64:65] op_sel_hi:[1,0]
	v_pk_fma_f32 v[184:185], v[242:243], v[184:185], v[250:251]
	v_pk_fma_f32 v[186:187], v[244:245], v[186:187], v[252:253]
	v_pk_fma_f32 v[188:189], v[246:247], v[188:189], v[180:181]
	v_pk_fma_f32 v[190:191], v[248:249], v[190:191], v[182:183]
	ds_read_b128 v[242:245], v230 offset:512
	ds_read_b128 v[246:249], v230 offset:528
	ds_read_b128 v[250:253], v230 offset:4608
	ds_read_b128 v[180:183], v230 offset:4624
	v_cvt_pk_bf16_f32 v184, v184, v185
	v_cvt_pk_bf16_f32 v185, v186, v187
	v_cvt_pk_bf16_f32 v186, v188, v189
	v_cvt_pk_bf16_f32 v187, v190, v191
	global_store_dwordx4 v[238:239], v[184:187], off offset:192
	s_nop 0
	s_waitcnt lgkmcnt(0)
	v_pk_mul_f32 v[184:185], v[200:201], v[64:65] op_sel_hi:[1,0]
	v_pk_mul_f32 v[186:187], v[202:203], v[64:65] op_sel_hi:[1,0]
	v_pk_mul_f32 v[188:189], v[196:197], v[64:65] op_sel_hi:[1,0]
	v_pk_mul_f32 v[190:191], v[198:199], v[64:65] op_sel_hi:[1,0]
	v_pk_fma_f32 v[184:185], v[242:243], v[184:185], v[250:251]
	v_pk_fma_f32 v[186:187], v[244:245], v[186:187], v[252:253]
	v_pk_fma_f32 v[188:189], v[246:247], v[188:189], v[180:181]
	v_pk_fma_f32 v[190:191], v[248:249], v[190:191], v[182:183]
	ds_read_b128 v[242:245], v230 offset:640
	ds_read_b128 v[246:249], v230 offset:656
	ds_read_b128 v[250:253], v230 offset:4736
	ds_read_b128 v[180:183], v230 offset:4752
	v_cvt_pk_bf16_f32 v184, v184, v185
	v_cvt_pk_bf16_f32 v185, v186, v187
	v_cvt_pk_bf16_f32 v186, v188, v189
	v_cvt_pk_bf16_f32 v187, v190, v191
	global_store_dwordx4 v[238:239], v[184:187], off offset:256
	s_nop 0
	s_waitcnt lgkmcnt(0)
	v_pk_mul_f32 v[184:185], v[208:209], v[64:65] op_sel_hi:[1,0]
	v_pk_mul_f32 v[186:187], v[210:211], v[64:65] op_sel_hi:[1,0]
	v_pk_mul_f32 v[188:189], v[204:205], v[64:65] op_sel_hi:[1,0]
	v_pk_mul_f32 v[190:191], v[206:207], v[64:65] op_sel_hi:[1,0]
	v_pk_fma_f32 v[184:185], v[242:243], v[184:185], v[250:251]
	v_pk_fma_f32 v[186:187], v[244:245], v[186:187], v[252:253]
	v_pk_fma_f32 v[188:189], v[246:247], v[188:189], v[180:181]
	v_pk_fma_f32 v[190:191], v[248:249], v[190:191], v[182:183]
	ds_read_b128 v[242:245], v230 offset:768
	ds_read_b128 v[246:249], v230 offset:784
	ds_read_b128 v[250:253], v230 offset:4864
	ds_read_b128 v[180:183], v230 offset:4880
	v_cvt_pk_bf16_f32 v184, v184, v185
	v_cvt_pk_bf16_f32 v185, v186, v187
	v_cvt_pk_bf16_f32 v186, v188, v189
	v_cvt_pk_bf16_f32 v187, v190, v191
	global_store_dwordx4 v[238:239], v[184:187], off offset:320
	s_nop 0
	s_waitcnt lgkmcnt(0)
	v_pk_mul_f32 v[184:185], v[212:213], v[64:65] op_sel_hi:[1,0]
	v_pk_mul_f32 v[186:187], v[214:215], v[64:65] op_sel_hi:[1,0]
	v_pk_mul_f32 v[188:189], v[216:217], v[64:65] op_sel_hi:[1,0]
	v_pk_mul_f32 v[190:191], v[218:219], v[64:65] op_sel_hi:[1,0]
	v_pk_fma_f32 v[184:185], v[242:243], v[184:185], v[250:251]
	v_pk_fma_f32 v[186:187], v[244:245], v[186:187], v[252:253]
	v_pk_fma_f32 v[188:189], v[246:247], v[188:189], v[180:181]
	v_pk_fma_f32 v[190:191], v[248:249], v[190:191], v[182:183]
	ds_read_b128 v[242:245], v230 offset:896
	ds_read_b128 v[246:249], v230 offset:912
	ds_read_b128 v[250:253], v230 offset:4992
	ds_read_b128 v[180:183], v230 offset:5008
	v_cvt_pk_bf16_f32 v184, v184, v185
	v_cvt_pk_bf16_f32 v185, v186, v187
	v_cvt_pk_bf16_f32 v186, v188, v189
	v_cvt_pk_bf16_f32 v187, v190, v191
	global_store_dwordx4 v[238:239], v[184:187], off offset:384
	s_nop 0
	s_waitcnt lgkmcnt(0)
	v_pk_mul_f32 v[184:185], v[224:225], v[64:65] op_sel_hi:[1,0]
	v_pk_mul_f32 v[186:187], v[226:227], v[64:65] op_sel_hi:[1,0]
	v_pk_mul_f32 v[188:189], v[220:221], v[64:65] op_sel_hi:[1,0]
	v_pk_mul_f32 v[190:191], v[222:223], v[64:65] op_sel_hi:[1,0]
	v_pk_fma_f32 v[184:185], v[242:243], v[184:185], v[250:251]
	v_pk_fma_f32 v[186:187], v[244:245], v[186:187], v[252:253]
	v_pk_fma_f32 v[188:189], v[246:247], v[188:189], v[180:181]
	v_pk_fma_f32 v[190:191], v[248:249], v[190:191], v[182:183]
	v_cvt_pk_bf16_f32 v184, v184, v185
	v_cvt_pk_bf16_f32 v185, v186, v187
	v_cvt_pk_bf16_f32 v186, v188, v189
	v_cvt_pk_bf16_f32 v187, v190, v191
	global_store_dwordx4 v[238:239], v[184:187], off offset:448
.Lp5n_c2:
	ds_bpermute_b32 v20, v25, v64
	v_cmp_lt_i32_e32 vcc, v23, v21
	v_xor_b32_e32 v25, 4, v133
	v_or_b32_e32 v30, s0, v122
	v_cndmask_b32_e32 v23, v133, v23, vcc
	v_lshlrev_b32_e32 v26, 2, v23
	s_waitcnt lgkmcnt(0)
	v_fma_f32 v16, v16, v20, v99
	ds_bpermute_b32 v20, v26, v16
	v_cmp_lt_i32_e32 vcc, v22, v21
	v_xor_b32_e32 v23, 8, v133
	v_lshlrev_b32_e32 v84, 2, v30
	v_cndmask_b32_e32 v22, v133, v22, vcc
	s_waitcnt lgkmcnt(0)
	v_max_f32_e32 v20, v20, v20
	v_lshlrev_b32_e32 v27, 2, v22
	v_max_f32_e32 v20, v16, v20
	ds_bpermute_b32 v22, v27, v20
	v_cmp_lt_i32_e32 vcc, v25, v21
	s_waitcnt lgkmcnt(0)
	v_max_f32_e32 v22, v22, v22
	v_cndmask_b32_e32 v25, v133, v25, vcc
	v_lshlrev_b32_e32 v29, 2, v25
	v_max_f32_e32 v20, v20, v22
	ds_bpermute_b32 v22, v29, v20
	v_lshlrev_b32_e32 v25, 2, v28
	ds_bpermute_b32 v25, v25, v64
	v_cmp_lt_i32_e32 vcc, v23, v21
	s_waitcnt lgkmcnt(0)
	v_fma_f32 v17, v17, v25, v99
	v_cndmask_b32_e32 v21, v133, v23, vcc
	v_lshlrev_b32_e32 v28, 2, v21
	v_max_f32_e32 v21, v22, v22
	v_max_f32_e32 v20, v20, v21
	ds_bpermute_b32 v22, v28, v20
	ds_bpermute_b32 v21, v26, v17
	s_waitcnt lgkmcnt(1)
	v_max_f32_e32 v22, v22, v22
	s_waitcnt lgkmcnt(0)
	v_max_f32_e32 v21, v21, v21
	v_max_f32_e32 v20, v20, v22
	v_sub_f32_e32 v16, v16, v20
	v_max_f32_e32 v20, v17, v21
	ds_bpermute_b32 v21, v27, v20
	v_mul_f32_e32 v22, 0x3fb8aa3b, v16
	v_fma_f32 v23, v16, s91, -v22
	v_rndne_f32_e32 v25, v22
	v_fmac_f32_e32 v23, 0x32a5705f, v16
	s_waitcnt lgkmcnt(0)
	v_max_f32_e32 v21, v21, v21
	v_max_f32_e32 v20, v20, v21
	ds_bpermute_b32 v21, v29, v20
	v_sub_f32_e32 v22, v22, v25
	v_add_f32_e32 v22, v22, v23
	v_exp_f32_e32 v22, v22
	v_cvt_i32_f32_e32 v23, v25
	s_waitcnt lgkmcnt(0)
	v_max_f32_e32 v21, v21, v21
	v_max_f32_e32 v20, v20, v21
	ds_bpermute_b32 v21, v28, v20
	v_ldexp_f32 v22, v22, v23
	v_cmp_ngt_f32_e32 vcc, s92, v16
	s_waitcnt lgkmcnt(0)
	v_max_f32_e32 v21, v21, v21
	v_max_f32_e32 v20, v20, v21
	v_sub_f32_e32 v17, v17, v20
	v_mul_f32_e32 v20, 0x3fb8aa3b, v17
	v_fma_f32 v21, v17, s91, -v20
	v_rndne_f32_e32 v23, v20
	v_fmac_f32_e32 v21, 0x32a5705f, v17
	v_sub_f32_e32 v20, v20, v23
	v_add_f32_e32 v20, v20, v21
	v_exp_f32_e32 v21, v20
	v_cvt_i32_f32_e32 v23, v23
	v_cndmask_b32_e32 v22, 0, v22, vcc
	v_cmp_nlt_f32_e32 vcc, s93, v16
	v_ldexp_f32 v21, v21, v23
	s_nop 0
	v_cndmask_b32_e32 v16, v134, v22, vcc
	v_cmp_ngt_f32_e32 vcc, s92, v17
	ds_bpermute_b32 v20, v26, v16
	s_nop 0
	v_cndmask_b32_e32 v21, 0, v21, vcc
	v_cmp_nlt_f32_e32 vcc, s93, v17
	s_nop 1
	v_cndmask_b32_e32 v17, v134, v21, vcc
	ds_bpermute_b32 v21, v26, v17
	s_waitcnt lgkmcnt(0)
	v_pk_add_f32 v[20:21], v[16:17], v[20:21]
	ds_bpermute_b32 v22, v27, v20
	ds_bpermute_b32 v23, v27, v21
	s_waitcnt lgkmcnt(0)
	v_pk_add_f32 v[20:21], v[20:21], v[22:23]
	v_or_b32_e32 v22, v24, v124
	v_lshlrev_b32_e32 v22, 2, v22
	ds_bpermute_b32 v25, v22, v64
	ds_bpermute_b32 v22, v29, v20
	ds_bpermute_b32 v23, v29, v21
	v_or_b32_e32 v24, v24, v125
	v_lshlrev_b32_e32 v24, 2, v24
	s_waitcnt lgkmcnt(2)
	v_fma_f32 v18, v18, v25, v99
	ds_bpermute_b32 v25, v26, v18
	s_waitcnt lgkmcnt(1)
	v_pk_add_f32 v[20:21], v[20:21], v[22:23]
	ds_bpermute_b32 v22, v28, v20
	ds_bpermute_b32 v23, v28, v21
	ds_bpermute_b32 v24, v24, v64
	s_waitcnt lgkmcnt(3)
	v_max_f32_e32 v25, v25, v25
	v_max_f32_e32 v25, v18, v25
	ds_bpermute_b32 v31, v27, v25
	s_waitcnt lgkmcnt(2)
	v_pk_add_f32 v[20:21], v[20:21], v[22:23]
	s_waitcnt lgkmcnt(1)
	v_fma_f32 v19, v19, v24, v99
	v_div_scale_f32 v32, s[0:1], v21, v21, v17
	s_waitcnt lgkmcnt(0)
	v_max_f32_e32 v22, v31, v31
	v_max_f32_e32 v25, v25, v22
	v_rcp_f32_e32 v33, v32
	ds_bpermute_b32 v31, v29, v25
	ds_bpermute_b32 v24, v26, v19
	v_lshl_add_u64 v[22:23], v[116:117], 0, v[84:85]
	v_fma_f32 v30, -v32, v33, 1.0
	v_fmac_f32_e32 v33, v30, v33
	s_waitcnt lgkmcnt(1)
	v_max_f32_e32 v30, v31, v31
	v_max_f32_e32 v25, v25, v30
	ds_bpermute_b32 v30, v28, v25
	s_waitcnt lgkmcnt(1)
	v_max_f32_e32 v24, v24, v24
	v_max_f32_e32 v24, v19, v24
	v_div_scale_f32 v31, vcc, v17, v21, v17
	s_waitcnt lgkmcnt(0)
	v_max_f32_e32 v30, v30, v30
	v_max_f32_e32 v25, v25, v30
	v_sub_f32_e32 v18, v18, v25
	ds_bpermute_b32 v25, v27, v24
	v_mul_f32_e32 v30, 0x3fb8aa3b, v18
	v_fma_f32 v35, v18, s91, -v30
	v_rndne_f32_e32 v36, v30
	v_fmac_f32_e32 v35, 0x32a5705f, v18
	s_waitcnt lgkmcnt(0)
	v_max_f32_e32 v25, v25, v25
	v_max_f32_e32 v24, v24, v25
	ds_bpermute_b32 v25, v29, v24
	v_sub_f32_e32 v30, v30, v36
	v_add_f32_e32 v30, v30, v35
	v_exp_f32_e32 v30, v30
	v_cvt_i32_f32_e32 v35, v36
	s_waitcnt lgkmcnt(0)
	v_max_f32_e32 v25, v25, v25
	v_max_f32_e32 v24, v24, v25
	ds_bpermute_b32 v25, v28, v24
	v_ldexp_f32 v30, v30, v35
	v_cmp_ngt_f32_e64 s[0:1], s92, v18
	v_mul_f32_e32 v34, v31, v33
	v_fma_f32 v36, -v32, v34, v31
	s_waitcnt lgkmcnt(0)
	v_max_f32_e32 v25, v25, v25
	v_max_f32_e32 v24, v24, v25
	v_sub_f32_e32 v19, v19, v24
	v_mul_f32_e32 v24, 0x3fb8aa3b, v19
	v_fma_f32 v25, v19, s91, -v24
	v_rndne_f32_e32 v35, v24
	v_fmac_f32_e32 v25, 0x32a5705f, v19
	v_sub_f32_e32 v24, v24, v35
	v_add_f32_e32 v24, v24, v25
	v_exp_f32_e32 v25, v24
	v_cvt_i32_f32_e32 v35, v35
	v_cndmask_b32_e64 v30, 0, v30, s[0:1]
	v_cmp_nlt_f32_e64 s[0:1], s93, v18
	v_fmac_f32_e32 v34, v36, v33
	v_ldexp_f32 v25, v25, v35
	v_cndmask_b32_e64 v18, v134, v30, s[0:1]
	v_cmp_ngt_f32_e64 s[0:1], s92, v19
	ds_bpermute_b32 v24, v26, v18
	s_nop 0
	v_cndmask_b32_e64 v25, 0, v25, s[0:1]
	v_cmp_nlt_f32_e64 s[0:1], s93, v19
	s_nop 1
	v_cndmask_b32_e64 v19, v134, v25, s[0:1]
	ds_bpermute_b32 v25, v26, v19
	v_fma_f32 v26, -v32, v34, v31
	v_div_fmas_f32 v30, v26, v33, v34
	v_div_fixup_f32 v17, v30, v21, v17
	v_div_scale_f32 v21, s[0:1], v20, v20, v16
	s_waitcnt lgkmcnt(0)
	v_pk_add_f32 v[24:25], v[18:19], v[24:25]
	ds_bpermute_b32 v26, v27, v24
	ds_bpermute_b32 v27, v27, v25
	v_rcp_f32_e32 v30, v21
	s_waitcnt lgkmcnt(0)
	v_pk_add_f32 v[24:25], v[24:25], v[26:27]
	ds_bpermute_b32 v26, v29, v24
	ds_bpermute_b32 v27, v29, v25
	v_fma_f32 v29, -v21, v30, 1.0
	v_fmac_f32_e32 v30, v29, v30
	v_div_scale_f32 v29, vcc, v16, v20, v16
	s_waitcnt lgkmcnt(0)
	v_pk_add_f32 v[24:25], v[24:25], v[26:27]
	ds_bpermute_b32 v26, v28, v24
	ds_bpermute_b32 v27, v28, v25
	v_mul_f32_e32 v28, v29, v30
	v_fma_f32 v31, -v21, v28, v29
	v_fmac_f32_e32 v28, v31, v30
	v_fma_f32 v21, -v21, v28, v29
	s_waitcnt lgkmcnt(0)
	v_pk_add_f32 v[24:25], v[24:25], v[26:27]
	v_div_fmas_f32 v21, v21, v30, v28
	v_div_scale_f32 v26, s[0:1], v25, v25, v19
	v_rcp_f32_e32 v27, v26
	v_div_fixup_f32 v16, v21, v20, v16
	v_fma_f32 v20, -v26, v27, 1.0
	v_fmac_f32_e32 v27, v20, v27
	v_div_scale_f32 v20, vcc, v19, v25, v19
	v_mul_f32_e32 v21, v20, v27
	v_fma_f32 v28, -v26, v21, v20
	v_fmac_f32_e32 v21, v28, v27
	v_fma_f32 v20, -v26, v21, v20
	v_div_scale_f32 v26, s[0:1], v24, v24, v18
	v_rcp_f32_e32 v28, v26
	v_div_fmas_f32 v20, v20, v27, v21
	v_div_fixup_f32 v19, v20, v25, v19
	v_fma_f32 v20, -v26, v28, 1.0
	v_fmac_f32_e32 v28, v20, v28
	v_div_scale_f32 v20, vcc, v18, v24, v18
	v_mul_f32_e32 v21, v20, v28
	v_fma_f32 v25, -v26, v21, v20
	v_fmac_f32_e32 v21, v25, v28
	v_fma_f32 v20, -v26, v21, v20
	v_div_fmas_f32 v20, v20, v28, v21
	v_div_fixup_f32 v18, v20, v24, v18
	global_store_dwordx4 v[22:23], v[16:19], off
	s_nop 1
	v_lshlrev_b32_e32 v16, 2, v133
	v_and_b32_e32 v65, 0x100, v16
	v_xor_b32_e32 v231, 0x8000, v231
	v_xor_b32_e32 v232, 0x8000, v232
	v_xor_b32_e32 v233, 0x8000, v233
	v_xor_b32_e32 v234, 0x8000, v234
	s_add_i32 s98, s98, 1
	s_cmp_lt_u32 s98, 8
	s_cbranch_scc1 .Lp5n_loop
	s_lshl_b32 s61, s100, 2
	s_add_i32 s61, s61, s99
	s_lshl_b32 s61, s61, 1
	s_lshl_b32 s62, s61, 4
	s_lshl_b32 s101, s94, 8
	s_add_i32 s62, s62, s101
	v_or_b32_e32 v130, s62, v120
	s_add_i32 s94, s94, s82
	s_add_i32 s62, s62, s63
	s_cmpk_gt_i32 s94, 0xff
	v_add_u32_e32 v130, s63, v130
	s_cbranch_scc0 .LBB0_738
